# combined: P4 permlane row sums + stale lgkmcnt waits removed from the U reduce spans (on top of U/V DPP-permlane reduces)
# speedup vs baseline: 1.0013x; 1.0013x over previous
.Lux_skip1:
	v_dot4c_i32_i8_e32 v138, v0, v64
	v_dot4c_i32_i8_e32 v178, v4, v64
	v_dot4c_i32_i8_e32 v185, v32, v64
	v_dot4c_i32_i8_e32 v186, v36, v64
	v_dot4c_i32_i8_e32 v138, v1, v65
	v_lshl_or_b32 v69, v69, 7, v137
	v_lshl_or_b32 v68, v68, 7, v174
	global_load_dwordx4 v[132:135], v68, s[14:15]
	global_load_dwordx4 v[128:131], v69, s[14:15]
	v_dot4c_i32_i8_e32 v178, v5, v65
	v_dot4c_i32_i8_e32 v185, v33, v65
	v_dot4c_i32_i8_e32 v186, v37, v65
	v_dot4c_i32_i8_e32 v138, v2, v66
	v_dot4c_i32_i8_e32 v178, v6, v66
	v_dot4c_i32_i8_e32 v185, v34, v66
	v_dot4c_i32_i8_e32 v186, v38, v66
	v_dot4c_i32_i8_e32 v138, v3, v67
	v_dot4c_i32_i8_e32 v178, v7, v67
	v_dot4c_i32_i8_e32 v185, v35, v67
	v_dot4c_i32_i8_e32 v186, v39, v67
	v_lshl_or_b32 v69, v70, 7, v174
	v_lshl_or_b32 v68, v71, 7, v137
	global_load_dwordx4 v[124:127], v69, s[14:15]
	global_load_dwordx4 v[120:123], v68, s[14:15]
	v_add_u32_dpp v215, v138, v138 row_ror:12 row_mask:0xf bank_mask:0x5
	v_add_u32_dpp v215, v185, v185 row_ror:4 row_mask:0xf bank_mask:0xa
	v_dot4_i32_i8 v180, v12, v64, 0
	v_dot4_i32_i8 v210, v44, v64, 0
	v_dot4c_i32_i8_e32 v180, v13, v65
	v_dot4_i32_i8 v181, v16, v64, 0
	v_lshl_or_b32 v69, v72, 7, v174
	v_lshl_or_b32 v68, v73, 7, v137
	global_load_dwordx4 v[116:119], v69, s[14:15]
	global_load_dwordx4 v[112:115], v68, s[14:15]
	v_dot4c_i32_i8_e32 v210, v45, v65
	v_dot4_i32_i8 v211, v48, v64, 0
	v_dot4c_i32_i8_e32 v180, v14, v66
	v_dot4c_i32_i8_e32 v181, v17, v65
	v_dot4c_i32_i8_e32 v210, v46, v66
	v_dot4c_i32_i8_e32 v211, v49, v65
	v_dot4c_i32_i8_e32 v180, v15, v67
	v_dot4c_i32_i8_e32 v181, v18, v66
	v_dot4c_i32_i8_e32 v210, v47, v67
	v_dot4c_i32_i8_e32 v211, v50, v66
	v_add_u32_dpp v178, v178, v178 row_ror:12 row_mask:0xf bank_mask:0x5
	v_add_u32_dpp v178, v186, v186 row_ror:4 row_mask:0xf bank_mask:0xa
	v_lshl_or_b32 v69, v74, 7, v174
	v_lshl_or_b32 v68, v75, 7, v137
	global_load_dwordx4 v[108:111], v69, s[14:15]
	global_load_dwordx4 v[104:107], v68, s[14:15]
	v_dot4c_i32_i8_e32 v181, v19, v67
	v_dot4c_i32_i8_e32 v211, v51, v67
	v_add_u32_dpp v185, v180, v180 row_ror:12 row_mask:0xf bank_mask:0x5
	v_add_u32_dpp v185, v210, v210 row_ror:4 row_mask:0xf bank_mask:0xa
	v_dot4_i32_i8 v179, v8, v64, 0
	v_dot4_i32_i8 v182, v20, v64, 0
	v_lshl_or_b32 v69, v76, 7, v174
	v_lshl_or_b32 v68, v77, 7, v137
	global_load_dwordx4 v[100:103], v69, s[14:15]
	global_load_dwordx4 v[96:99], v68, s[14:15]
	v_dot4_i32_i8 v187, v40, v64, 0
	v_dot4_i32_i8 v212, v52, v64, 0
	v_dot4c_i32_i8_e32 v179, v9, v65
	v_dot4c_i32_i8_e32 v182, v21, v65
	v_dot4_i32_i8 v183, v24, v64, 0
	v_dot4c_i32_i8_e32 v187, v41, v65
	v_lshl_or_b32 v69, v78, 7, v174
	v_lshl_or_b32 v68, v79, 7, v137
	global_load_dwordx4 v[92:95], v69, s[14:15]
	global_load_dwordx4 v[88:91], v68, s[14:15]
	v_dot4c_i32_i8_e32 v212, v53, v65
	v_dot4_i32_i8 v213, v56, v64, 0
	v_dot4c_i32_i8_e32 v179, v10, v66
	v_dot4c_i32_i8_e32 v182, v22, v66
	v_dot4c_i32_i8_e32 v183, v25, v65
	v_dot4_i32_i8 v184, v28, v64, 0
	v_dot4c_i32_i8_e32 v187, v42, v66
	v_dot4c_i32_i8_e32 v212, v54, v66
	v_dot4c_i32_i8_e32 v213, v57, v65
	v_lshl_or_b32 v68, v81, 7, v137
	v_lshl_or_b32 v69, v80, 7, v174
	global_load_dwordx4 v[84:87], v69, s[14:15]
	global_load_dwordx4 v[76:79], v68, s[14:15]
	v_dot4_i32_i8 v214, v60, v64, 0
	v_dot4c_i32_i8_e32 v179, v11, v67
	v_dot4c_i32_i8_e32 v182, v23, v67
	v_dot4c_i32_i8_e32 v183, v26, v66
	v_dot4c_i32_i8_e32 v184, v29, v65
	v_dot4c_i32_i8_e32 v187, v43, v67
	v_dot4c_i32_i8_e32 v212, v55, v67
	v_dot4c_i32_i8_e32 v213, v58, v66
	v_dot4c_i32_i8_e32 v214, v61, v65
	v_dot4c_i32_i8_e32 v183, v27, v67
	v_dot4c_i32_i8_e32 v184, v30, v66
	v_dot4c_i32_i8_e32 v213, v59, v67
	v_lshl_or_b32 v68, v83, 7, v137
	v_lshl_or_b32 v69, v82, 7, v174
	global_load_dwordx4 v[72:75], v69, s[14:15]
	global_load_dwordx4 v[68:71], v68, s[14:15]
	v_add_u32_e32 v231, s99, v230
	ds_read_b128 v[80:83], v231
	v_dot4c_i32_i8_e32 v214, v62, v66
	v_add_u32_dpp v179, v179, v179 row_ror:12 row_mask:0xf bank_mask:0x5
	v_add_u32_dpp v179, v187, v187 row_ror:4 row_mask:0xf bank_mask:0xa
	v_dot4c_i32_i8_e32 v184, v31, v67
	v_dot4c_i32_i8_e32 v214, v63, v67
	v_mov_b32_e32 v180, v185
	v_add_u32_dpp v181, v181, v181 row_ror:12 row_mask:0xf bank_mask:0x5
	v_add_u32_dpp v181, v211, v211 row_ror:4 row_mask:0xf bank_mask:0xa
	v_add_u32_dpp v185, v183, v183 row_ror:12 row_mask:0xf bank_mask:0x5
	v_add_u32_dpp v185, v213, v213 row_ror:4 row_mask:0xf bank_mask:0xa
	v_add_u32_dpp v182, v182, v182 row_ror:12 row_mask:0xf bank_mask:0x5
	v_add_u32_dpp v182, v212, v212 row_ror:4 row_mask:0xf bank_mask:0xa
	v_mov_b32_e32 v138, v215
	v_mov_b32_e32 v183, v185
	v_add_u32_dpp v184, v184, v184 row_ror:12 row_mask:0xf bank_mask:0x5
	v_add_u32_dpp v184, v214, v214 row_ror:4 row_mask:0xf bank_mask:0xa
	v_add_u32_dpp v234, v138, v138 quad_perm:[2,3,0,1] row_mask:0xf bank_mask:0xf
	v_add_u32_dpp v235, v181, v181 quad_perm:[2,3,0,1] row_mask:0xf bank_mask:0xf
	v_cndmask_b32_e64 v138, v235, v234, s[4:5]
	v_add_u32_dpp v234, v178, v178 quad_perm:[2,3,0,1] row_mask:0xf bank_mask:0xf
	v_add_u32_dpp v235, v182, v182 quad_perm:[2,3,0,1] row_mask:0xf bank_mask:0xf
	v_cndmask_b32_e64 v181, v235, v234, s[4:5]
	v_add_u32_dpp v234, v179, v179 quad_perm:[2,3,0,1] row_mask:0xf bank_mask:0xf
	v_add_u32_dpp v235, v183, v183 quad_perm:[2,3,0,1] row_mask:0xf bank_mask:0xf
	v_cndmask_b32_e64 v178, v235, v234, s[4:5]
	v_add_u32_dpp v234, v180, v180 quad_perm:[2,3,0,1] row_mask:0xf bank_mask:0xf
	v_add_u32_dpp v235, v184, v184 quad_perm:[2,3,0,1] row_mask:0xf bank_mask:0xf
	v_cndmask_b32_e64 v179, v235, v234, s[4:5]
	s_add_i32 s1, s61, 0xffffff00
	v_add_u32_dpp v234, v138, v138 quad_perm:[1,0,3,2] row_mask:0xf bank_mask:0xf
	v_add_u32_dpp v235, v178, v178 quad_perm:[1,0,3,2] row_mask:0xf bank_mask:0xf
	v_cndmask_b32_e64 v138, v235, v234, s[6:7]
	s_and_b32 s1, s1, 0x700
	v_mov_b32_e32 v178, v138
	v_add_u32_dpp v234, v181, v181 quad_perm:[1,0,3,2] row_mask:0xf bank_mask:0xf
	v_add_u32_dpp v235, v179, v179 quad_perm:[1,0,3,2] row_mask:0xf bank_mask:0xf
	v_cndmask_b32_e64 v138, v235, v234, s[6:7]
	s_cmp_gt_u32 s0, 15
	v_mov_b32_e32 v179, v138
	s_cselect_b64 s[14:15], -1, 0
	s_cmp_lt_u32 s0, 16
	v_lshl_add_u32 v138, s1, 2, v190
	s_cbranch_scc1 .LBB0_926
	ds_read_b64 v[180:181], v138
	s_waitcnt lgkmcnt(0)
	v_add_u32_e32 v178, v180, v178
	v_add_u32_e32 v179, v181, v179

.LBB0_928:
	s_waitcnt vmcnt(0)
	v_dot4_i32_i8 v138, v132, v80, 0
	global_load_dwordx4 v[0:3], v0, s[16:17]
	v_dot4_i32_i8 v132, v128, v80, 0
	v_dot4_i32_i8 v128, v124, v80, 0
	v_dot4_i32_i8 v124, v120, v80, 0
	global_load_dwordx4 v[4:7], v4, s[16:17]
	v_dot4_i32_i8 v120, v116, v80, 0
	v_dot4_i32_i8 v116, v112, v80, 0
	global_load_dwordx4 v[8:11], v8, s[16:17]
	v_dot4_i32_i8 v112, v108, v80, 0
	v_dot4_i32_i8 v108, v104, v80, 0
	v_dot4_i32_i8 v104, v100, v80, 0
	global_load_dwordx4 v[12:15], v12, s[16:17]
	v_dot4_i32_i8 v100, v96, v80, 0
	v_dot4_i32_i8 v96, v92, v80, 0
	v_dot4_i32_i8 v92, v88, v80, 0
	global_load_dwordx4 v[16:19], v16, s[16:17]
	v_dot4_i32_i8 v88, v84, v80, 0
	v_dot4c_i32_i8_e32 v138, v133, v81
	v_dot4c_i32_i8_e32 v104, v101, v81
	global_load_dwordx4 v[20:23], v20, s[16:17]
	v_dot4_i32_i8 v84, v76, v80, 0
	v_dot4c_i32_i8_e32 v138, v134, v82
	v_dot4c_i32_i8_e32 v132, v129, v81
	v_dot4c_i32_i8_e32 v104, v102, v82
	global_load_dwordx4 v[24:27], v24, s[16:17]
	v_dot4c_i32_i8_e32 v100, v97, v81
	v_dot4_i32_i8 v76, v72, v80, 0
	v_dot4c_i32_i8_e32 v138, v135, v83
	v_dot4c_i32_i8_e32 v132, v130, v82
	global_load_dwordx4 v[28:31], v28, s[16:17]
	v_dot4c_i32_i8_e32 v128, v125, v81
	v_dot4c_i32_i8_e32 v104, v103, v83
	v_dot4c_i32_i8_e32 v100, v98, v82
	v_dot4c_i32_i8_e32 v96, v93, v81
	v_dot4_i32_i8 v72, v68, v80, 0
	global_load_dwordx4 v[32:35], v32, s[16:17]
	v_dot4c_i32_i8_e32 v132, v131, v83
	v_dot4c_i32_i8_e32 v128, v126, v82
	v_dot4c_i32_i8_e32 v124, v121, v81
	v_dot4c_i32_i8_e32 v100, v99, v83
	v_dot4c_i32_i8_e32 v96, v94, v82
	global_load_dwordx4 v[36:39], v36, s[16:17]
	v_dot4c_i32_i8_e32 v92, v89, v81
	v_dot4c_i32_i8_e32 v72, v69, v81
	v_dot4c_i32_i8_e32 v128, v127, v83
	v_dot4c_i32_i8_e32 v124, v122, v82
	global_load_dwordx4 v[40:43], v40, s[16:17]
	v_dot4c_i32_i8_e32 v120, v117, v81
	v_dot4c_i32_i8_e32 v96, v95, v83
	v_dot4c_i32_i8_e32 v92, v90, v82
	v_dot4c_i32_i8_e32 v88, v85, v81
	v_dot4c_i32_i8_e32 v72, v70, v82
	global_load_dwordx4 v[44:47], v44, s[16:17]
	v_dot4c_i32_i8_e32 v124, v123, v83
	v_dot4c_i32_i8_e32 v120, v118, v82
	v_dot4c_i32_i8_e32 v116, v113, v81
	global_load_dwordx4 v[48:51], v48, s[16:17]
	v_dot4c_i32_i8_e32 v92, v91, v83
	v_dot4c_i32_i8_e32 v88, v86, v82
	v_dot4c_i32_i8_e32 v84, v77, v81
	v_dot4c_i32_i8_e32 v72, v71, v83
	global_load_dwordx4 v[52:55], v52, s[16:17]
	v_dot4c_i32_i8_e32 v120, v119, v83
	v_dot4c_i32_i8_e32 v116, v114, v82
	v_dot4c_i32_i8_e32 v88, v87, v83
	v_dot4c_i32_i8_e32 v84, v78, v82
	v_dot4c_i32_i8_e32 v76, v73, v81
	global_load_dwordx4 v[56:59], v56, s[16:17]
	v_dot4c_i32_i8_e32 v116, v115, v83
	v_dot4c_i32_i8_e32 v84, v79, v83
	v_dot4c_i32_i8_e32 v76, v74, v82
	global_load_dwordx4 v[60:63], v60, s[16:17]
	v_dot4c_i32_i8_e32 v76, v75, v83
	v_add_u32_dpp v68, v138, v138 row_ror:12 row_mask:0xf bank_mask:0x5
	v_add_u32_dpp v68, v104, v104 row_ror:4 row_mask:0xf bank_mask:0xa
	v_add_u32_dpp v69, v132, v132 row_ror:12 row_mask:0xf bank_mask:0x5
	v_add_u32_dpp v69, v100, v100 row_ror:4 row_mask:0xf bank_mask:0xa
	v_add_u32_dpp v70, v128, v128 row_ror:12 row_mask:0xf bank_mask:0x5
	v_add_u32_dpp v70, v96, v96 row_ror:4 row_mask:0xf bank_mask:0xa
	v_dot4c_i32_i8_e32 v112, v109, v81
	v_dot4c_i32_i8_e32 v108, v105, v81
	v_add_u32_dpp v71, v124, v124 row_ror:12 row_mask:0xf bank_mask:0x5
	v_add_u32_dpp v71, v92, v92 row_ror:4 row_mask:0xf bank_mask:0xa
	v_dot4c_i32_i8_e32 v112, v110, v82
	v_dot4c_i32_i8_e32 v108, v106, v82
	v_add_u32_dpp v73, v120, v120 row_ror:12 row_mask:0xf bank_mask:0x5
	v_add_u32_dpp v73, v88, v88 row_ror:4 row_mask:0xf bank_mask:0xa
	v_dot4c_i32_i8_e32 v112, v111, v83
	v_dot4c_i32_i8_e32 v108, v107, v83
	v_add_u32_dpp v74, v116, v116 row_ror:12 row_mask:0xf bank_mask:0x5
	v_add_u32_dpp v74, v84, v84 row_ror:4 row_mask:0xf bank_mask:0xa
	v_add_u32_dpp v75, v112, v112 row_ror:12 row_mask:0xf bank_mask:0x5
	v_add_u32_dpp v75, v76, v76 row_ror:4 row_mask:0xf bank_mask:0xa
	v_add_u32_dpp v72, v72, v72 row_ror:4 row_mask:0xf bank_mask:0xa
	v_add_u32_dpp v72, v108, v108 row_ror:12 row_mask:0xf bank_mask:0x5
	v_add_u32_dpp v234, v68, v68 quad_perm:[2,3,0,1] row_mask:0xf bank_mask:0xf
	v_add_u32_dpp v235, v73, v73 quad_perm:[2,3,0,1] row_mask:0xf bank_mask:0xf
	v_cndmask_b32_e64 v68, v235, v234, s[4:5]
	v_add_u32_dpp v234, v69, v69 quad_perm:[2,3,0,1] row_mask:0xf bank_mask:0xf
	v_add_u32_dpp v235, v74, v74 quad_perm:[2,3,0,1] row_mask:0xf bank_mask:0xf
	v_cndmask_b32_e64 v73, v235, v234, s[4:5]
	v_add_u32_dpp v234, v70, v70 quad_perm:[2,3,0,1] row_mask:0xf bank_mask:0xf
	v_add_u32_dpp v235, v75, v75 quad_perm:[2,3,0,1] row_mask:0xf bank_mask:0xf
	v_cndmask_b32_e64 v70, v235, v234, s[4:5]
	v_add_u32_dpp v234, v71, v71 quad_perm:[2,3,0,1] row_mask:0xf bank_mask:0xf
	v_add_u32_dpp v235, v72, v72 quad_perm:[2,3,0,1] row_mask:0xf bank_mask:0xf
	v_cndmask_b32_e64 v71, v235, v234, s[4:5]
	v_mov_b32_e32 v69, v73
	v_add_u32_dpp v234, v68, v68 quad_perm:[1,0,3,2] row_mask:0xf bank_mask:0xf
	v_add_u32_dpp v235, v70, v70 quad_perm:[1,0,3,2] row_mask:0xf bank_mask:0xf
	v_cndmask_b32_e64 v68, v235, v234, s[6:7]
	v_add_u32_dpp v234, v69, v69 quad_perm:[1,0,3,2] row_mask:0xf bank_mask:0xf
	v_add_u32_dpp v235, v71, v71 quad_perm:[1,0,3,2] row_mask:0xf bank_mask:0xf
	v_cndmask_b32_e64 v69, v235, v234, s[6:7]
	s_andn2_b64 vcc, exec, s[14:15]
	v_lshl_add_u32 v70, s65, 2, v190
	s_cbranch_vccnz .LBB0_923
	ds_read_b64 v[72:73], v70
	s_waitcnt lgkmcnt(0)
	v_add_u32_e32 v68, v72, v68
	v_add_u32_e32 v69, v73, v69
	s_branch .LBB0_923
